# nt cache policy also on the final RMSNorm phase's once-read loads and never-re-read output stores
# speedup vs baseline: 1.0084x; 1.0014x over previous
; __device__ __forceinline__ float wave_sum(float v) { return xadd32(sum32(v)); }
; __device__ __forceinline__ int opaque_tid() { int t = threadIdx.x; asm volatile("" : "+v"(t)); return t; }
; __device__ __forceinline__ void final_phase(const float* x, const float* gain, float* out) {
;     const int tid_ = opaque_tid(); const int lane = tid_ & 63, wave = __builtin_amdgcn_readfirstlane(tid_ >> 6);
;     const int gw = blockIdx.x * NWAVES + wave, NGW = gridDim.x * NWAVES;
;     f32x4 gn[4];
; #pragma unroll
;     for (int j = 0; j < 4; ++j) gn[j] = *(const f32x4*)(gain + 4 * lane + 256 * j);
;     int row = gw; f32x4 v[4], vn[4];
;     if (row < RL) {
; #pragma unroll
;         for (int j = 0; j < 4; ++j) v[j] = *(const f32x4*)(x + (size_t)row * DM + 4 * lane + 256 * j); }
;     for (; row < RL; row += NGW) {
;         const int rn = row + NGW;
;         if (rn < RL) {
; #pragma unroll
;             for (int j = 0; j < 4; ++j) vn[j] = *(const f32x4*)(x + (size_t)rn * DM + 4 * lane + 256 * j); }
;         float ss = 0.f;
; #pragma unroll
;         for (int j = 0; j < 4; ++j) ss += (v[j][0] * v[j][0] + v[j][1] * v[j][1]) + (v[j][2] * v[j][2] + v[j][3] * v[j][3]);
;         const float rstd = __builtin_amdgcn_rsqf(wave_sum(ss) * (1.0f / DM) + EPS);
; #pragma unroll
;         for (int j = 0; j < 4; ++j) *(f32x4*)(out + (size_t)row * DM + 4 * lane + 256 * j) = v[j] * rstd * gn[j];
; #pragma unroll
;         for (int j = 0; j < 4; ++j) v[j] = vn[j];
;     }
; }
.LBB0_1216:
	v_readlane_b32 s1, v252, 50
	v_readfirstlane_b32 s0, v192
	s_ashr_i32 s0, s0, 6
	s_add_i32 s0, s0, s1
	s_cmpk_gt_i32 s0, 0x7fff
	s_cbranch_scc1 .LBB0_1221
	s_ashr_i32 s1, s0, 31
	s_lshl_b64 s[2:3], s[0:1], 12
	v_readlane_b32 s4, v252, 53
	v_lshlrev_b32_e32 v0, 4, v192
	v_readlane_b32 s5, v252, 54
	s_add_u32 s4, s4, s2
	v_and_b32_e32 v28, 0x3f0, v0
	s_addc_u32 s5, s5, s3
	global_load_dwordx4 v[0:3], v28, s[60:61] nt
	global_load_dwordx4 v[4:7], v28, s[60:61] offset:1024 nt
	global_load_dwordx4 v[8:11], v28, s[60:61] offset:2048 nt
	global_load_dwordx4 v[12:15], v28, s[60:61] offset:3072 nt
	global_load_dwordx4 v[32:35], v28, s[4:5] nt
	global_load_dwordx4 v[24:27], v28, s[4:5] offset:1024 nt
	global_load_dwordx4 v[20:23], v28, s[4:5] offset:2048 nt
	global_load_dwordx4 v[16:19], v28, s[4:5] offset:3072 nt
	s_add_u32 s2, s62, s2
	s_addc_u32 s3, s63, s3
	s_add_i32 s4, s0, s88
	s_ashr_i32 s5, s4, 31
	s_lshl_b64 s[4:5], s[4:5], 12
	v_and_b32_e32 v28, 63, v192
	v_mov_b32_e32 v49, 0
	s_add_u32 s4, s96, s4
	v_lshlrev_b32_e32 v48, 4, v28
	s_addc_u32 s5, s97, s5
	v_mov_b32_e32 v50, 0x358637bd
	v_mov_b32_e32 v28, v49
	v_mov_b32_e32 v29, v49
	v_mov_b32_e32 v30, v49
	v_mov_b32_e32 v31, v49
	v_mov_b32_e32 v36, v49
	v_mov_b32_e32 v37, v49
	v_mov_b32_e32 v38, v49
	v_mov_b32_e32 v39, v49
	v_mov_b32_e32 v40, v49
	v_mov_b32_e32 v41, v49
	v_mov_b32_e32 v42, v49
	v_mov_b32_e32 v43, v49
	v_mov_b32_e32 v44, v49
	v_mov_b32_e32 v45, v49
	v_mov_b32_e32 v46, v49
	v_mov_b32_e32 v47, v49
	s_branch .LBB0_1219
.LBB0_1218:
	s_waitcnt vmcnt(3)
	v_mul_f32_e32 v51, v33, v33
	v_mul_f32_e32 v52, v35, v35
	v_fmac_f32_e32 v51, v32, v32
	v_fmac_f32_e32 v52, v34, v34
	v_add_f32_e32 v51, v51, v52
	s_waitcnt vmcnt(2)
	v_mul_f32_e32 v52, v25, v25
	v_mul_f32_e32 v53, v27, v27
	v_fmac_f32_e32 v52, v24, v24
	v_fmac_f32_e32 v53, v26, v26
	v_add_f32_e32 v52, v52, v53
	v_add_f32_e32 v51, v51, v52
	s_waitcnt vmcnt(1)
	v_mul_f32_e32 v52, v21, v21
	v_mul_f32_e32 v53, v23, v23
	v_fmac_f32_e32 v52, v20, v20
	v_fmac_f32_e32 v53, v22, v22
	v_add_f32_e32 v52, v52, v53
	v_add_f32_e32 v51, v52, v51
	s_waitcnt vmcnt(0)
	v_mul_f32_e32 v52, v17, v17
	v_mul_f32_e32 v53, v19, v19
	v_fmac_f32_e32 v52, v16, v16
	v_fmac_f32_e32 v53, v18, v18
	v_add_f32_e32 v52, v52, v53
	v_add_f32_e32 v51, v52, v51
	ds_swizzle_b32 v52, v51 offset:swizzle(SWAP,1)
	v_lshl_add_u64 v[54:55], s[2:3], 0, v[48:49]
	s_add_u32 s2, s2, s64
	s_addc_u32 s3, s3, s65
	s_add_u32 s4, s4, s64
	s_waitcnt lgkmcnt(0)
	v_add_f32_e32 v51, v51, v52
	ds_swizzle_b32 v52, v51 offset:swizzle(SWAP,2)
	s_addc_u32 s5, s5, s65
	s_andn2_b64 vcc, exec, s[6:7]
	s_waitcnt lgkmcnt(0)
	v_add_f32_e32 v51, v51, v52
	ds_swizzle_b32 v52, v51 offset:swizzle(SWAP,4)
	s_waitcnt lgkmcnt(0)
	v_add_f32_e32 v51, v51, v52
	ds_swizzle_b32 v52, v51 offset:swizzle(SWAP,8)
	s_waitcnt lgkmcnt(0)
	v_add_f32_e32 v51, v51, v52
	ds_swizzle_b32 v52, v51 offset:swizzle(SWAP,16)
	s_waitcnt lgkmcnt(0)
	v_add_f32_e32 v51, v51, v52
	v_mov_b32_e32 v52, v51
	s_nop 1
	v_permlane32_swap_b32_e32 v51, v52
	v_add_f32_e32 v51, v51, v52
	v_fmamk_f32 v51, v51, 0x3a800000, v50
	v_rsq_f32_e32 v52, v51
	s_nop 0
	v_mul_f32_e32 v32, v32, v52
	v_mul_f32_e32 v33, v33, v52
	v_mul_f32_e32 v34, v34, v52
	v_mul_f32_e32 v35, v35, v52
	v_mul_f32_e32 v56, v24, v52
	v_mul_f32_e32 v57, v25, v52
	v_mul_f32_e32 v58, v26, v52
	v_mul_f32_e32 v59, v27, v52
	v_mul_f32_e32 v26, v2, v34
	v_mul_f32_e32 v27, v3, v35
	v_mul_f32_e32 v24, v0, v32
	v_mul_f32_e32 v25, v1, v33
	v_mul_f32_e32 v20, v20, v52
	v_mul_f32_e32 v21, v21, v52
	v_mul_f32_e32 v22, v22, v52
	v_mul_f32_e32 v23, v23, v52
	v_mul_f32_e32 v16, v16, v52
	v_mul_f32_e32 v17, v17, v52
	v_mul_f32_e32 v18, v18, v52
	v_mul_f32_e32 v19, v19, v52
	global_store_dwordx4 v[54:55], v[24:27], off nt
	v_mul_f32_e32 v22, v10, v22
	v_mul_f32_e32 v23, v11, v23
	v_mul_f32_e32 v20, v8, v20
	v_mul_f32_e32 v21, v9, v21
	v_mul_f32_e32 v26, v6, v58
	v_mul_f32_e32 v27, v7, v59
	v_mul_f32_e32 v24, v4, v56
	v_mul_f32_e32 v25, v5, v57
	v_mul_f32_e32 v18, v14, v18
	v_mul_f32_e32 v19, v15, v19
	v_mul_f32_e32 v16, v12, v16
	v_mul_f32_e32 v17, v13, v17
	global_store_dwordx4 v[54:55], v[24:27], off offset:1024 nt
	global_store_dwordx4 v[54:55], v[20:23], off offset:2048 nt
	global_store_dwordx4 v[54:55], v[16:19], off offset:3072 nt
	v_mov_b32_e32 v32, v28
	v_mov_b32_e32 v33, v29
	v_mov_b32_e32 v34, v30
	v_mov_b32_e32 v35, v31
	v_mov_b32_e32 v24, v36
	v_mov_b32_e32 v25, v37
	v_mov_b32_e32 v26, v38
	v_mov_b32_e32 v27, v39
	v_mov_b32_e32 v20, v40
	v_mov_b32_e32 v21, v41
	v_mov_b32_e32 v22, v42
	v_mov_b32_e32 v23, v43
	v_mov_b32_e32 v16, v44
	v_mov_b32_e32 v17, v45
	v_mov_b32_e32 v18, v46
	v_mov_b32_e32 v19, v47
	s_cbranch_vccz .LBB0_1221
.LBB0_1219:
	s_add_i32 s0, s0, s88
	s_cmpk_gt_i32 s0, 0x7fff
	s_cselect_b64 s[6:7], -1, 0
	s_and_b64 vcc, exec, s[6:7]
	s_cbranch_vccnz .LBB0_1218
	v_lshl_add_u64 v[28:29], s[4:5], 0, v[48:49]
	v_add_co_u32_e32 v52, vcc, 0xa000000, v28
	s_nop 1
	v_addc_co_u32_e32 v53, vcc, 0, v29, vcc
	global_load_dwordx4 v[28:31], v[52:53], off nt
	global_load_dwordx4 v[36:39], v[52:53], off offset:1024 nt
	global_load_dwordx4 v[40:43], v[52:53], off offset:2048 nt
	global_load_dwordx4 v[44:47], v[52:53], off offset:3072 nt
	s_branch .LBB0_1218
